# windowed attention: full-window key blocks skip the per-element window test (ALiBi sub+fma only)
# speedup vs baseline: 1.0162x; 1.0116x over previous
.LBB0_928:
	s_add_i32 s0, s13, s14
	v_add_u32_e32 v244, 0, v239
	v_add_u32_e32 v0, 0x20400, v244
	ds_read_b128 v[4:7], v0
	v_add_u32_e32 v0, 0x20480, v244
	s_cmp_lt_i32 s0, s11
	ds_read_b128 v[8:11], v0
	s_cselect_b64 s[6:7], -1, 0
	s_cmp_gt_i32 s0, s12
	v_add_u32_e32 v243, s13, v241
	s_cselect_b64 s[16:17], -1, 0
	v_subrev_u32_e32 v0, 59, v243
	s_or_b64 s[6:7], s[6:7], s[16:17]
	s_cbranch_scc0 .Lwin_full
	s_waitcnt lgkmcnt(1)
	v_sub_f32_e32 v3, v4, v237
	v_cmp_gt_u32_e32 vcc, v0, v236
	v_subrev_u32_e32 v2, 27, v243
	v_fma_f32 v3, v231, |v3|, v96
	s_and_b64 vcc, s[6:7], vcc
	s_waitcnt lgkmcnt(0)
	v_sub_f32_e32 v4, v8, v237
	v_cndmask_b32_e32 v0, v3, v225, vcc
	v_cmp_gt_u32_e32 vcc, v2, v236
	v_fma_f32 v4, v231, |v4|, v80
	s_and_b64 vcc, s[6:7], vcc
	v_sub_f32_e32 v3, v5, v237
	v_subrev_u32_e32 v5, 58, v243
	v_cndmask_b32_e32 v2, v4, v225, vcc
	v_cmp_gt_u32_e32 vcc, v5, v236
	v_fma_f32 v3, v231, |v3|, v97
	s_and_b64 vcc, s[6:7], vcc
	v_subrev_u32_e32 v5, 26, v243
	v_sub_f32_e32 v4, v9, v237
	v_cndmask_b32_e32 v3, v3, v225, vcc
	v_cmp_gt_u32_e32 vcc, v5, v236
	v_fma_f32 v4, v231, |v4|, v81
	s_and_b64 vcc, s[6:7], vcc
	v_subrev_u32_e32 v8, 57, v243
	v_cndmask_b32_e32 v5, v4, v225, vcc
	v_sub_f32_e32 v4, v6, v237
	v_cmp_gt_u32_e32 vcc, v8, v236
	v_fma_f32 v4, v231, |v4|, v98
	s_and_b64 vcc, s[6:7], vcc
	v_subrev_u32_e32 v8, 25, v243
	v_sub_f32_e32 v6, v10, v237
	v_cndmask_b32_e32 v4, v4, v225, vcc
	v_cmp_gt_u32_e32 vcc, v8, v236
	v_fma_f32 v6, v231, |v6|, v82
	s_and_b64 vcc, s[6:7], vcc
	v_subrev_u32_e32 v9, 56, v243
	v_cndmask_b32_e32 v6, v6, v225, vcc
	v_sub_f32_e32 v7, v7, v237
	v_cmp_gt_u32_e32 vcc, v9, v236
	v_fma_f32 v7, v231, |v7|, v99
	s_and_b64 vcc, s[6:7], vcc
	v_subrev_u32_e32 v9, 24, v243
	v_sub_f32_e32 v8, v11, v237
	v_cndmask_b32_e32 v7, v7, v225, vcc
	v_cmp_gt_u32_e32 vcc, v9, v236
	v_fma_f32 v8, v231, |v8|, v83
	s_and_b64 vcc, s[6:7], vcc
	v_cndmask_b32_e32 v9, v8, v225, vcc
	v_add_u32_e32 v8, 0x20420, v244
	ds_read_b128 v[12:15], v8
	v_add_u32_e32 v8, 0x204a0, v244
	ds_read_b128 v[80:83], v8
	v_subrev_u32_e32 v8, 51, v243
	v_cmp_gt_u32_e32 vcc, v8, v236
	s_waitcnt lgkmcnt(1)
	v_sub_f32_e32 v11, v12, v237
	v_subrev_u32_e32 v10, 19, v243
	v_fma_f32 v11, v231, |v11|, v100
	s_and_b64 vcc, s[6:7], vcc
	s_waitcnt lgkmcnt(0)
	v_sub_f32_e32 v12, v80, v237
	v_cndmask_b32_e32 v8, v11, v225, vcc
	v_cmp_gt_u32_e32 vcc, v10, v236
	v_fma_f32 v12, v231, |v12|, v84
	s_and_b64 vcc, s[6:7], vcc
	v_sub_f32_e32 v11, v13, v237
	v_subrev_u32_e32 v13, 50, v243
	v_cndmask_b32_e32 v10, v12, v225, vcc
	v_cmp_gt_u32_e32 vcc, v13, v236
	v_fma_f32 v11, v231, |v11|, v101
	s_and_b64 vcc, s[6:7], vcc
	v_subrev_u32_e32 v13, 18, v243
	v_sub_f32_e32 v12, v81, v237
	v_cndmask_b32_e32 v11, v11, v225, vcc
	v_cmp_gt_u32_e32 vcc, v13, v236
	v_fma_f32 v12, v231, |v12|, v85
	s_and_b64 vcc, s[6:7], vcc
	v_subrev_u32_e32 v80, 49, v243
	v_cndmask_b32_e32 v13, v12, v225, vcc
	v_sub_f32_e32 v12, v14, v237
	v_cmp_gt_u32_e32 vcc, v80, v236
	v_fma_f32 v12, v231, |v12|, v102
	s_and_b64 vcc, s[6:7], vcc
	v_subrev_u32_e32 v80, 17, v243
	v_sub_f32_e32 v14, v82, v237
	v_cndmask_b32_e32 v12, v12, v225, vcc
	v_cmp_gt_u32_e32 vcc, v80, v236
	v_fma_f32 v14, v231, |v14|, v86
	s_and_b64 vcc, s[6:7], vcc
	v_subrev_u32_e32 v81, 48, v243
	v_cndmask_b32_e32 v14, v14, v225, vcc
	v_sub_f32_e32 v15, v15, v237
	v_cmp_gt_u32_e32 vcc, v81, v236
	v_fma_f32 v15, v231, |v15|, v103
	s_and_b64 vcc, s[6:7], vcc
	v_add_u32_e32 v81, -16, v243
	v_sub_f32_e32 v80, v83, v237
	v_cndmask_b32_e32 v15, v15, v225, vcc
	v_cmp_gt_u32_e32 vcc, v81, v236
	v_fma_f32 v80, v231, |v80|, v87
	s_and_b64 vcc, s[6:7], vcc
	v_cndmask_b32_e32 v81, v80, v225, vcc
	v_add_u32_e32 v80, 0x20440, v244
	ds_read_b128 v[96:99], v80
	v_add_u32_e32 v80, 0x204c0, v244
	ds_read_b128 v[100:103], v80
	v_subrev_u32_e32 v80, 43, v243
	v_cmp_gt_u32_e32 vcc, v80, v236
	s_waitcnt lgkmcnt(1)
	v_sub_f32_e32 v82, v96, v237
	v_add_u32_e32 v83, -11, v243
	v_fma_f32 v82, v231, |v82|, v104
	s_and_b64 vcc, s[6:7], vcc
	s_waitcnt lgkmcnt(0)
	v_sub_f32_e32 v84, v100, v237
	v_cndmask_b32_e32 v82, v82, v225, vcc
	v_cmp_gt_u32_e32 vcc, v83, v236
	v_fma_f32 v84, v231, |v84|, v88
	s_and_b64 vcc, s[6:7], vcc
	v_subrev_u32_e32 v85, 42, v243
	v_cndmask_b32_e32 v84, v84, v225, vcc
	v_sub_f32_e32 v80, v97, v237
	v_cmp_gt_u32_e32 vcc, v85, v236
	v_fma_f32 v80, v231, |v80|, v105
	s_and_b64 vcc, s[6:7], vcc
	v_cndmask_b32_e32 v85, v80, v225, vcc
	v_add_u32_e32 v80, -10, v243
	v_sub_f32_e32 v83, v101, v237
	v_cmp_gt_u32_e32 vcc, v80, v236
	v_fma_f32 v83, v231, |v83|, v89
	s_and_b64 vcc, s[6:7], vcc
	v_subrev_u32_e32 v86, 41, v243
	v_cndmask_b32_e32 v87, v83, v225, vcc
	v_sub_f32_e32 v80, v98, v237
	v_cmp_gt_u32_e32 vcc, v86, v236
	v_fma_f32 v80, v231, |v80|, v106
	s_and_b64 vcc, s[6:7], vcc
	v_cndmask_b32_e32 v86, v80, v225, vcc
	v_add_u32_e32 v80, -9, v243
	v_sub_f32_e32 v83, v102, v237
	v_cmp_gt_u32_e32 vcc, v80, v236
	v_fma_f32 v83, v231, |v83|, v90
	s_and_b64 vcc, s[6:7], vcc
	v_subrev_u32_e32 v89, 40, v243
	v_cndmask_b32_e32 v80, v83, v225, vcc
	v_sub_f32_e32 v83, v99, v237
	v_cmp_gt_u32_e32 vcc, v89, v236
	v_fma_f32 v83, v231, |v83|, v107
	s_and_b64 vcc, s[6:7], vcc
	v_cndmask_b32_e32 v89, v83, v225, vcc
	v_add_u32_e32 v83, -8, v243
	v_sub_f32_e32 v88, v103, v237
	v_cmp_gt_u32_e32 vcc, v83, v236
	v_fma_f32 v88, v231, |v88|, v91
	s_and_b64 vcc, s[6:7], vcc
	v_cndmask_b32_e32 v83, v88, v225, vcc
	v_add_u32_e32 v88, 0x20460, v244
	ds_read_b128 v[100:103], v88
	v_add_u32_e32 v88, 0x204e0, v244
	ds_read_b128 v[96:99], v88
	v_subrev_u32_e32 v88, 35, v243
	v_cmp_gt_u32_e32 vcc, v88, v236
	s_waitcnt lgkmcnt(1)
	v_sub_f32_e32 v91, v100, v237
	v_add_u32_e32 v90, -3, v243
	v_fma_f32 v91, v231, |v91|, v108
	s_waitcnt lgkmcnt(0)
	v_sub_f32_e32 v96, v96, v237
	s_and_b64 vcc, s[6:7], vcc
	v_fma_f32 v96, v231, |v96|, v92
	v_cndmask_b32_e32 v92, v91, v225, vcc
	v_cmp_gt_u32_e32 vcc, v90, v236
	v_sub_f32_e32 v91, v97, v237
	s_and_b64 vcc, s[6:7], vcc
	v_fma_f32 v91, v231, |v91|, v93
	v_subrev_u32_e32 v93, 34, v243
	v_cndmask_b32_e32 v88, v96, v225, vcc
	v_sub_f32_e32 v90, v101, v237
	v_cmp_gt_u32_e32 vcc, v93, v236
	v_fma_f32 v90, v231, |v90|, v109
	s_and_b64 vcc, s[6:7], vcc
	v_cndmask_b32_e32 v93, v90, v225, vcc
	v_add_u32_e32 v90, -2, v243
	v_cmp_gt_u32_e32 vcc, v90, v236
	v_sub_f32_e32 v96, v98, v237
	s_and_b64 vcc, s[6:7], vcc
	v_fma_f32 v96, v231, |v96|, v94
	v_subrev_u32_e32 v94, 33, v243
	v_cndmask_b32_e32 v91, v91, v225, vcc
	v_sub_f32_e32 v90, v102, v237
	v_cmp_gt_u32_e32 vcc, v94, v236
	v_fma_f32 v90, v231, |v90|, v110
	s_and_b64 vcc, s[6:7], vcc
	v_cndmask_b32_e32 v94, v90, v225, vcc
	v_add_u32_e32 v90, -1, v243
	v_cmp_gt_u32_e32 vcc, v90, v236
	v_sub_f32_e32 v97, v99, v237
	s_and_b64 vcc, s[6:7], vcc
	v_fma_f32 v95, v231, |v97|, v95
	v_subrev_u32_e32 v97, 32, v243
	v_cndmask_b32_e32 v90, v96, v225, vcc
	v_sub_f32_e32 v96, v103, v237
	v_cmp_gt_u32_e32 vcc, v97, v236
	v_fma_f32 v96, v231, |v96|, v111
	s_and_b64 vcc, s[6:7], vcc
	v_cndmask_b32_e32 v97, v96, v225, vcc
.Lwin_join:
	v_max_f32_e32 v96, v0, v2
	v_max3_f32 v96, v96, v3, v5
	v_max3_f32 v96, v96, v4, v6
	v_max3_f32 v96, v96, v7, v9
	v_max3_f32 v96, v96, v8, v10
	v_max3_f32 v96, v96, v11, v13
	v_max3_f32 v96, v96, v12, v14
	v_max3_f32 v96, v96, v15, v81
	v_max3_f32 v96, v96, v82, v84
	v_max3_f32 v96, v96, v85, v87
	v_max3_f32 v96, v96, v86, v80
	v_max3_f32 v96, v96, v89, v83
	v_cmp_gt_u32_e32 vcc, v243, v236
	v_max3_f32 v96, v96, v92, v88
	s_and_b64 vcc, s[6:7], vcc
	v_max3_f32 v96, v96, v93, v91
	v_cndmask_b32_e32 v95, v95, v225, vcc
	v_max3_f32 v96, v96, v94, v90
	v_max3_f32 v96, v96, v97, v95
	v_mov_b32_e32 v98, v96
	s_nop 1
	v_permlane32_swap_b32_e32 v96, v98
	v_max_f32_e32 v98, v98, v98
	v_max_f32_e32 v96, v96, v96
	v_max_f32_e32 v96, v96, v98
	v_cmp_lt_f32_e32 vcc, s69, v96
	s_cbranch_vccz .LBB0_925
	v_max_f32_e32 v64, v96, v96
	v_max_f32_e32 v65, 0, v64
	v_exp_f32_e64 v64, -v65
	v_add_f32_e32 v242, v242, v65
	v_sub_f32_e32 v0, v0, v65
	v_sub_f32_e32 v2, v2, v65
	v_pk_mul_f32 v[46:47], v[46:47], v[64:65] op_sel_hi:[1,0]
	v_pk_mul_f32 v[44:45], v[44:45], v[64:65] op_sel_hi:[1,0]
	v_pk_mul_f32 v[42:43], v[42:43], v[64:65] op_sel_hi:[1,0]
	v_pk_mul_f32 v[40:41], v[40:41], v[64:65] op_sel_hi:[1,0]
	v_pk_mul_f32 v[38:39], v[38:39], v[64:65] op_sel_hi:[1,0]
	v_pk_mul_f32 v[36:37], v[36:37], v[64:65] op_sel_hi:[1,0]
	v_pk_mul_f32 v[34:35], v[34:35], v[64:65] op_sel_hi:[1,0]
	v_pk_mul_f32 v[32:33], v[32:33], v[64:65] op_sel_hi:[1,0]
	v_pk_mul_f32 v[62:63], v[62:63], v[64:65] op_sel_hi:[1,0]
	v_pk_mul_f32 v[60:61], v[60:61], v[64:65] op_sel_hi:[1,0]
	v_pk_mul_f32 v[58:59], v[58:59], v[64:65] op_sel_hi:[1,0]
	v_pk_mul_f32 v[56:57], v[56:57], v[64:65] op_sel_hi:[1,0]
	v_pk_mul_f32 v[54:55], v[54:55], v[64:65] op_sel_hi:[1,0]
	v_pk_mul_f32 v[52:53], v[52:53], v[64:65] op_sel_hi:[1,0]
	v_pk_mul_f32 v[50:51], v[50:51], v[64:65] op_sel_hi:[1,0]
	v_pk_mul_f32 v[48:49], v[48:49], v[64:65] op_sel_hi:[1,0]
	v_mul_f32_e32 v235, v235, v64
	v_xor_b32_e32 v64, 0x80000000, v242
	v_sub_f32_e32 v3, v3, v65
	v_sub_f32_e32 v5, v5, v65
	v_sub_f32_e32 v4, v4, v65
	v_sub_f32_e32 v6, v6, v65
	v_sub_f32_e32 v7, v7, v65
	v_sub_f32_e32 v9, v9, v65
	v_sub_f32_e32 v8, v8, v65
	v_sub_f32_e32 v10, v10, v65
	v_sub_f32_e32 v11, v11, v65
	v_sub_f32_e32 v13, v13, v65
	v_sub_f32_e32 v12, v12, v65
	v_sub_f32_e32 v14, v14, v65
	v_sub_f32_e32 v15, v15, v65
	v_sub_f32_e32 v81, v81, v65
	v_sub_f32_e32 v82, v82, v65
	v_sub_f32_e32 v84, v84, v65
	v_sub_f32_e32 v85, v85, v65
	v_sub_f32_e32 v87, v87, v65
	v_sub_f32_e32 v86, v86, v65
	v_sub_f32_e32 v80, v80, v65
	v_sub_f32_e32 v89, v89, v65
	v_sub_f32_e32 v83, v83, v65
	v_sub_f32_e32 v92, v92, v65
	v_sub_f32_e32 v88, v88, v65
	v_sub_f32_e32 v93, v93, v65
	v_sub_f32_e32 v91, v91, v65
	v_sub_f32_e32 v94, v94, v65
	v_sub_f32_e32 v90, v90, v65
	v_sub_f32_e32 v97, v97, v65
	v_sub_f32_e32 v95, v95, v65
	v_mov_b32_e32 v65, v64
	v_mov_b32_e32 v66, v64
	v_mov_b32_e32 v67, v64
	v_mov_b32_e32 v68, v64
	v_mov_b32_e32 v69, v64
	v_mov_b32_e32 v70, v64
	v_mov_b32_e32 v71, v64
	v_mov_b32_e32 v72, v64
	v_mov_b32_e32 v73, v64
	v_mov_b32_e32 v74, v64
	v_mov_b32_e32 v75, v64
	v_mov_b32_e32 v76, v64
	v_mov_b32_e32 v77, v64
	v_mov_b32_e32 v78, v64
	v_mov_b32_e32 v79, v64
	s_branch .LBB0_925
.Lwin_full:
	s_waitcnt lgkmcnt(1)
	v_sub_f32_e32 v3, v4, v237
	v_fma_f32 v0, v231, |v3|, v96
	s_waitcnt lgkmcnt(0)
	v_sub_f32_e32 v4, v8, v237
	v_fma_f32 v2, v231, |v4|, v80
	v_sub_f32_e32 v3, v5, v237
	v_fma_f32 v3, v231, |v3|, v97
	v_sub_f32_e32 v4, v9, v237
	v_fma_f32 v5, v231, |v4|, v81
	v_sub_f32_e32 v4, v6, v237
	v_fma_f32 v4, v231, |v4|, v98
	v_sub_f32_e32 v6, v10, v237
	v_fma_f32 v6, v231, |v6|, v82
	v_sub_f32_e32 v7, v7, v237
	v_fma_f32 v7, v231, |v7|, v99
	v_sub_f32_e32 v8, v11, v237
	v_fma_f32 v9, v231, |v8|, v83
	v_add_u32_e32 v8, 0x20420, v244
	ds_read_b128 v[12:15], v8
	v_add_u32_e32 v8, 0x204a0, v244
	ds_read_b128 v[80:83], v8
	s_waitcnt lgkmcnt(1)
	v_sub_f32_e32 v11, v12, v237
	v_fma_f32 v8, v231, |v11|, v100
	s_waitcnt lgkmcnt(0)
	v_sub_f32_e32 v12, v80, v237
	v_fma_f32 v10, v231, |v12|, v84
	v_sub_f32_e32 v11, v13, v237
	v_fma_f32 v11, v231, |v11|, v101
	v_sub_f32_e32 v12, v81, v237
	v_fma_f32 v13, v231, |v12|, v85
	v_sub_f32_e32 v12, v14, v237
	v_fma_f32 v12, v231, |v12|, v102
	v_sub_f32_e32 v14, v82, v237
	v_fma_f32 v14, v231, |v14|, v86
	v_sub_f32_e32 v15, v15, v237
	v_fma_f32 v15, v231, |v15|, v103
	v_sub_f32_e32 v80, v83, v237
	v_fma_f32 v81, v231, |v80|, v87
	v_add_u32_e32 v80, 0x20440, v244
	ds_read_b128 v[96:99], v80
	v_add_u32_e32 v80, 0x204c0, v244
	ds_read_b128 v[100:103], v80
	s_waitcnt lgkmcnt(1)
	v_sub_f32_e32 v82, v96, v237
	v_fma_f32 v82, v231, |v82|, v104
	s_waitcnt lgkmcnt(0)
	v_sub_f32_e32 v84, v100, v237
	v_fma_f32 v84, v231, |v84|, v88
	v_sub_f32_e32 v80, v97, v237
	v_fma_f32 v85, v231, |v80|, v105
	v_sub_f32_e32 v83, v101, v237
	v_fma_f32 v87, v231, |v83|, v89
	v_sub_f32_e32 v80, v98, v237
	v_fma_f32 v86, v231, |v80|, v106
	v_sub_f32_e32 v83, v102, v237
	v_fma_f32 v80, v231, |v83|, v90
	v_sub_f32_e32 v83, v99, v237
	v_fma_f32 v89, v231, |v83|, v107
	v_sub_f32_e32 v88, v103, v237
	v_fma_f32 v83, v231, |v88|, v91
	v_add_u32_e32 v88, 0x20460, v244
	ds_read_b128 v[100:103], v88
	v_add_u32_e32 v88, 0x204e0, v244
	ds_read_b128 v[96:99], v88
	s_waitcnt lgkmcnt(1)
	v_sub_f32_e32 v91, v100, v237
	v_fma_f32 v91, v231, |v91|, v108
	s_waitcnt lgkmcnt(0)
	v_sub_f32_e32 v96, v96, v237
	v_fma_f32 v88, v231, |v96|, v92
	v_mov_b32_e32 v92, v91
	v_sub_f32_e32 v91, v97, v237
	v_fma_f32 v91, v231, |v91|, v93
	v_sub_f32_e32 v90, v101, v237
	v_fma_f32 v93, v231, |v90|, v109
	v_sub_f32_e32 v96, v98, v237
	v_fma_f32 v96, v231, |v96|, v94
	v_sub_f32_e32 v90, v102, v237
	v_fma_f32 v94, v231, |v90|, v110
	v_sub_f32_e32 v97, v99, v237
	v_fma_f32 v95, v231, |v97|, v95
	v_mov_b32_e32 v90, v96
	v_sub_f32_e32 v96, v103, v237
	v_fma_f32 v96, v231, |v96|, v111
	v_mov_b32_e32 v97, v96
	s_branch .Lwin_join
